# v12 + static s_setprio 1 for waves 4-7 during attn0/1/2 and index phases
# baseline (speedup 1.0000x reference)
; #define PH(k) if (p.ph_lo <= (k) && (k) < p.ph_hi)
;     ...
;     float lam = 0.f;
;     if (MODE == 0) {
;         float d1 = 0.f, d2 = 0.f;
;         for (int i = 0; i < 64; ++i) { d1 += p.in[4][i] * p.in[5][i]; d2 += p.in[6][i] * p.in[7][i]; }
;         lam = expf(d1) - expf(d2) + 0.2f;
;     }
; __global__ void __launch_bounds__(NTHREADS) fwd_megakernel(Params p) {
;     ...
;     PH(3) { attn_phase<0>(p, lds); attn_phase<1>(p, lds); }
.LBB0_1246:
	v_cmp_gt_i32_e32 vcc, 4, v1
	v_cmp_lt_i32_e64 s[2:3], 3, v5
	s_and_b64 s[0:1], vcc, s[2:3]
	s_and_saveexec_b64 s[72:73], s[0:1]
	s_cbranch_execz .LBB0_1391
	v_readfirstlane_b32 s32, v0
	s_nop 3
	s_cmp_lt_u32 s32, 0x100
	s_cbranch_scc1 .Lprio_skip_a01
	s_setprio 1
.Lprio_skip_a01:
	s_load_dwordx8 s[4:11], s[88:89], 0x20
	v_mov_b32_e32 v1, 0
	s_mov_b64 s[2:3], 0
	v_mov_b32_e32 v2, 0
	v_mov_b32_e32 v3, v1

; #define SYNC(k) if (p.ph_lo <= (k) && (k) + 1 < p.ph_hi) { if ((k) == 0) grid.sync(); else gbar(bctr, bgen, gridDim.x); }
; DI void gbar(unsigned* ctr, unsigned& gen, unsigned G) {
;     asm volatile("s_waitcnt vmcnt(0)" ::: "memory");
;     __syncthreads();
;     gen += 1;
;     if (threadIdx.x == 0) {
;         __builtin_amdgcn_fence(__ATOMIC_RELEASE, "agent");
;         asm volatile("s_waitcnt vmcnt(0)" ::: "memory");
;         __hip_atomic_fetch_add(ctr, 1u, __ATOMIC_RELAXED, __HIP_MEMORY_SCOPE_AGENT);
;         while (__hip_atomic_load(ctr, __ATOMIC_RELAXED, __HIP_MEMORY_SCOPE_AGENT) < gen * G) __builtin_amdgcn_s_sleep(32);
; __global__ void __launch_bounds__(NTHREADS) fwd_megakernel(Params p) {
;     ...
;     SYNC(3)
.LBB0_1391:
	s_or_b64 exec, exec, s[72:73]
	s_setprio 0
	v_cmp_gt_i32_e32 vcc, 4, v1
	v_cmp_lt_i32_e64 s[2:3], 4, v5
	s_and_b64 s[0:1], vcc, s[2:3]
	s_and_saveexec_b64 s[2:3], s[0:1]
	s_cbranch_execz .LBB0_1400
	s_waitcnt vmcnt(0)
	v_and_b32_e32 v2, 0x3ff, v0
	v_add_u32_e32 v210, 1, v210
	v_cmp_eq_u32_e32 vcc, 0, v2
	s_waitcnt vmcnt(0)
	s_barrier
	s_and_saveexec_b64 s[4:5], vcc
	s_cbranch_execz .LBB0_1399
	s_mov_b64 s[6:7], exec
	buffer_wbl2 sc1
	s_waitcnt vmcnt(0)
	v_mbcnt_lo_u32_b32 v1, s6, 0
	v_mbcnt_hi_u32_b32 v1, s7, v1
	v_cmp_eq_u32_e32 vcc, 0, v1
	s_and_saveexec_b64 s[8:9], vcc
	s_cbranch_execz .LBB0_1395
	s_bcnt1_i32_b64 s0, s[6:7]
	v_mov_b32_e32 v1, 0
	v_mov_b32_e32 v2, s0
	global_atomic_add v1, v2, s[62:63]

; #define PH(k) if (p.ph_lo <= (k) && (k) < p.ph_hi)
; DI void phase_index(const Params& p, unsigned char* lds) {
;     constexpr int NUNITS = 4 * 256;
;     constexpr int TILE_OFF = 65536, STAGE_B = 36864, INFO_OFF = 65536 + 2 * 36864;
;     const int tid = threadIdx.x, lane = tid & 63, wid = tid >> 6, r32 = lane & 31, hh = lane >> 5;
;     const int lrow = tid >> 3, lkc = tid & 7;
;     const int G = gridDim.x;
;     unsigned char* ws = p.ws;
;     const bf16_t* P = (const bf16_t*)(ws + WS_PBUF);
;     const bf16_t* ikb = (const bf16_t*)(ws + WS_IKB);
;     const float* iw = (const float*)(ws + WS_IW);
;     u64* bitmask = (u64*)(ws + WS_BITMASK);
;     unsigned* hist = (unsigned*)lds;
;     int* info = (int*)(lds + INFO_OFF);
;     for (int it = 0; it * G < NUNITS; ++it) {
;         const int pos = (it & 1) ? (G - 1 - (int)blockIdx.x) : (int)blockIdx.x;
;         const int u = it * G + pos;
;         if (u >= NUNITS) continue;
;         const int qblk = 255 - (u >> 2), b = u & 3;
;         const int t0 = qblk * 32;
;         const int nt = (t0 >> 6) + 1;
;         const int nst = (nt + 3) >> 2;
;         bf16x8 qf[4];
;         {
;             const bf16_t* qp = P + (size_t)(b * SEQ + t0 + 4 * wid + (r32 >> 3)) * P1_PITCH + 3072 + (r32 & 7) * 64 + 8 * hh;
; #pragma unroll
;             for (int ks = 0; ks < 4; ++ks) qf[ks] = *(const bf16x8*)(qp + 16 * ks);
;         }
;         f32x4 wq[4];
; #pragma unroll
;         for (int q = 0; q < 4; ++q) wq[q] = *(const f32x4*)(iw + (size_t)(b * SEQ + t0 + 4 * wid + q) * 8 + 4 * hh);
;         const bf16_t* srcp = ikb + (size_t)(b * SEQ + lrow) * 64 + lkc * 8;
;         const unsigned st_off = TILE_OFF + lrow * 144 + lkc * 16;
;         const unsigned rd_off = TILE_OFF + r32 * 144 + hh * 16;
;         int b1v[2] = {0, 0}, tauv[2] = {0, 0};
;         int rq[4] = {0, 0, 0, 0}, cntq[4] = {0, 0, 0, 0};
;         const unsigned hbase0 = (unsigned)(4 * wid + 2 * hh) * 2048u;
;         const int tq0 = t0 + 4 * wid + 2 * hh;
;         u64 Gm[4], Em[4];
;         int cntA[2] = {0, 0}; int hiv[2] = {0, 0}, sbv[2] = {8, 8}, kshv[2] = {12, 12};
; __global__ void __launch_bounds__(NTHREADS) fwd_megakernel(Params p) {
;     ...
;     PH(9) phase_index(p, lds);
.LBB0_2554:
	s_or_b64 exec, exec, s[2:3]
	v_cmp_gt_i32_e32 vcc, 10, v1
	v_cmp_lt_i32_e64 s[2:3], 9, v5
	v_bfe_u32 v107, v0, 5, 1
	s_and_b64 s[0:1], vcc, s[2:3]
	v_bfe_u32 v171, v0, 3, 7
	v_and_b32_e32 v194, 31, v0
	v_lshlrev_b32_e32 v82, 3, v107
	v_lshlrev_b32_e32 v84, 4, v107
	s_and_saveexec_b64 s[2:3], s[0:1]
	s_cbranch_execz .LBB0_3580
	v_readfirstlane_b32 s32, v0
	s_nop 3
	s_cmp_lt_u32 s32, 0x100
	s_cbranch_scc1 .Lprio_skip_idx
	s_setprio 1
.Lprio_skip_idx:
	s_add_u32 s40, s42, 0x1d200000
	v_mov_b32_e32 v87, 0
	s_addc_u32 s41, s43, 0
	s_not_b32 s0, s33
	v_mov_b32_e32 v85, v87
	s_add_i32 s78, s86, s0
	v_lshl_add_u64 v[4:5], s[42:43], 0, v[84:85]
	s_mov_b64 s[0:1], 0x1f600000
	v_lshl_add_u64 v[88:89], v[4:5], 0, s[0:1]
	v_lshlrev_b32_e32 v4, 4, v0
	v_and_b32_e32 v86, 0x70, v4
	v_lshl_add_u64 v[4:5], s[42:43], 0, v[86:87]
	s_mov_b64 s[0:1], 0x1f200000
	v_writelane_b32 v255, s2, 4
	v_and_b32_e32 v1, 63, v0
	v_and_b32_e32 v3, 0x3ff, v0
	v_lshl_add_u64 v[90:91], v[4:5], 0, s[0:1]
	s_movk_i32 s0, 0x90
	v_writelane_b32 v255, s3, 5
	s_waitcnt vmcnt(0)
	v_lshlrev_b32_e32 v118, 2, v6
	v_lshlrev_b32_e32 v2, 6, v3
	v_cmp_eq_u32_e64 s[2:3], 0, v3
	v_lshl_add_u32 v3, v6, 13, 0
	v_lshlrev_b32_e32 v120, 4, v1
	v_mad_u32_u24 v8, v171, s0, 0
	s_mov_b32 s0, 0x10000
	v_add_u32_e32 v121, v3, v120
	v_add3_u32 v122, v8, v86, s0
	v_and_b32_e32 v8, 32, v0
	v_lshl_add_u32 v123, v107, 12, v3
	s_add_i32 s79, 0, 0x22000
	v_or_b32_e32 v3, 1, v118
	v_cmp_eq_u32_e64 s[4:5], 0, v8
	v_lshl_add_u32 v140, v6, 4, s79
	v_lshlrev_b32_e32 v6, 11, v3
	v_lshlrev_b32_e32 v8, 5, v1
	v_lshl_add_u32 v142, v3, 4, s79
	v_mul_i32_i24_e32 v143, -12, v3
	v_or_b32_e32 v3, 2, v118
	v_lshl_or_b32 v85, v107, 1, v118
	v_add3_u32 v141, 0, v6, v8
	v_lshlrev_b32_e32 v6, 11, v3
	v_lshl_add_u32 v145, v3, 4, s79
	v_mul_i32_i24_e32 v146, -12, v3
	v_or_b32_e32 v3, 3, v118
	v_mul_u32_u24_e32 v7, 0x90, v194
	v_add3_u32 v144, 0, v6, v8
	v_lshlrev_b32_e32 v6, 11, v3
	v_lshl_add_u32 v148, v3, 4, s79
	v_mul_i32_i24_e32 v149, -12, v3
	v_or_b32_e32 v3, 1, v85
	v_and_b32_e32 v2, 0x1c0, v2
	v_cmp_eq_u32_e64 s[6:7], 63, v1
	v_cmp_gt_u32_e64 s[8:9], 62, v1
	v_cmp_gt_u32_e64 s[10:11], 60, v1
	v_cmp_gt_u32_e64 s[12:13], 56, v1
	v_cmp_gt_u32_e64 s[14:15], 48, v1
	v_cmp_gt_u32_e64 s[16:17], 32, v1
	v_cmp_eq_u32_e64 s[18:19], 0, v1
	v_lshl_add_u32 v152, v3, 4, s79
	v_mul_i32_i24_e32 v3, -12, v3
	v_cmp_eq_u32_e64 s[20:21], 1, v1
	v_cmp_eq_u32_e64 s[22:23], 2, v1
	v_cmp_eq_u32_e64 s[24:25], 3, v1
	v_add3_u32 v153, v7, v84, 0
	s_mov_b64 s[0:1], 0x1f20e000
	v_mbcnt_lo_u32_b32 v1, -1, 0
	v_bfe_u32 v119, v0, 3, 2
	s_mov_b32 s37, 0
	v_or_b32_e32 v124, 15, v120
	v_or_b32_e32 v125, 14, v120
	v_or_b32_e32 v126, 13, v120
	v_or_b32_e32 v127, 12, v120
	v_or_b32_e32 v128, 11, v120
	v_or_b32_e32 v129, 10, v120
	v_or_b32_e32 v130, 9, v120
	v_or_b32_e32 v131, 8, v120
	v_or_b32_e32 v132, 7, v120
	v_or_b32_e32 v133, 6, v120
	v_or_b32_e32 v134, 5, v120
	v_or_b32_e32 v135, 4, v120
	v_or_b32_e32 v136, 3, v120
	v_or_b32_e32 v137, 2, v120
	v_or_b32_e32 v138, 1, v120
	v_and_b32_e32 v139, 0x1c0, v0
	v_add3_u32 v147, 0, v6, v8
	v_lshl_add_u32 v150, v85, 4, s79
	v_mul_i32_i24_e32 v151, -12, v85
	v_add_u32_e32 v154, 0x10000, v153
	v_lshl_add_u64 v[92:93], v[4:5], 0, s[0:1]
	v_lshlrev_b32_e32 v155, 7, v171
	v_add_u32_e32 v156, 0x11200, v153
	s_movk_i32 s80, 0x6000
	v_lshlrev_b32_e32 v86, 1, v2
	v_lshlrev_b32_e32 v94, 1, v82
	s_add_i32 s81, 0, 0x22200
	s_mov_b64 s[44:45], 0x2000
	s_mov_b64 s[46:47], 0x4000
	s_mov_b64 s[48:49], 0x6000
	s_brev_b32 s82, 1
	s_movk_i32 s83, 0x100
	s_movk_i32 s84, 0x80
	s_movk_i32 s85, 0x7f
	s_movk_i32 s87, 0x400
	v_mov_b32_e32 v157, 1
	v_add_u32_e32 v158, v152, v3
	s_movk_i32 s88, 0x2400
	s_movk_i32 s89, 0xff
	v_mov_b32_e32 v159, 10
	v_mbcnt_hi_u32_b32 v160, -1, v1
	s_mov_b32 s0, 0
	s_mov_b32 s90, 0
	s_branch .LBB0_2558

; #define SYNC(k) if (p.ph_lo <= (k) && (k) + 1 < p.ph_hi) { if ((k) == 0) grid.sync(); else gbar(bctr, bgen, gridDim.x); }
; DI void gbar(unsigned* ctr, unsigned& gen, unsigned G) {
;     asm volatile("s_waitcnt vmcnt(0)" ::: "memory");
;     __syncthreads();
;     gen += 1;
;     if (threadIdx.x == 0) {
;         __builtin_amdgcn_fence(__ATOMIC_RELEASE, "agent");
;         asm volatile("s_waitcnt vmcnt(0)" ::: "memory");
;         __hip_atomic_fetch_add(ctr, 1u, __ATOMIC_RELAXED, __HIP_MEMORY_SCOPE_AGENT);
;         while (__hip_atomic_load(ctr, __ATOMIC_RELAXED, __HIP_MEMORY_SCOPE_AGENT) < gen * G) __builtin_amdgcn_s_sleep(32);
; __global__ void __launch_bounds__(NTHREADS) fwd_megakernel(Params p) {
;     ...
;     SYNC(9)
.LBB0_3580:
	s_or_b64 exec, exec, s[2:3]
	s_setprio 0
	v_cmp_gt_i32_e32 vcc, 10, v1
	v_cmp_lt_i32_e64 s[2:3], 10, v5
	s_and_b64 s[0:1], vcc, s[2:3]
	s_and_saveexec_b64 s[2:3], s[0:1]
	s_cbranch_execz .LBB0_3589
	s_waitcnt vmcnt(0)
	v_and_b32_e32 v2, 0x3ff, v0
	v_add_u32_e32 v210, 1, v210
	v_cmp_eq_u32_e32 vcc, 0, v2
	s_waitcnt vmcnt(0)
	s_barrier
	s_and_saveexec_b64 s[4:5], vcc
	s_cbranch_execz .LBB0_3588
	s_mov_b64 s[6:7], exec
	buffer_wbl2 sc1
	s_waitcnt vmcnt(0)
	v_mbcnt_lo_u32_b32 v1, s6, 0
	v_mbcnt_hi_u32_b32 v1, s7, v1
	v_cmp_eq_u32_e32 vcc, 0, v1
	s_and_saveexec_b64 s[8:9], vcc
	s_cbranch_execz .LBB0_3584
	s_bcnt1_i32_b64 s0, s[6:7]
	v_mov_b32_e32 v1, 0
	v_mov_b32_e32 v2, s0
	global_atomic_add v1, v2, s[62:63]

; #define PH(k) if (p.ph_lo <= (k) && (k) < p.ph_hi)
;     ...
;         f32x16 o[DVB];
; #pragma unroll
;         for (int db = 0; db < DVB; ++db)
; #pragma unroll
;             for (int i = 0; i < 16; ++i) o[db][i] = 0.f;
;         float m = -1e30f, l = 0.f;
;         constexpr bool DEEP = (MODE != 0);
;         u32x4 rgE[NJ], rgO[NJ]; float ckrE = 0.f, ckrO = 0.f;
;         auto gload = [&](u32x4 (&rg)[NJ], float& ckr, int t) {
; #pragma unroll
;             for (int j = 0; j < NJ; ++j) rg[j] = *(const u32x4*)(src[j] + (size_t)t * step[j]);
;             if (MODE == 1 && tid < 64) ckr = ckp[t * 64 + tid];
;         };
;         auto lstore = [&](const u32x4 (&rg)[NJ], const float ckr, int stg) {
;             unsigned char* sb = lds + stg * STG;
; #pragma unroll
;             for (int j = 0; j < NJ; ++j) {
;                 if (j < NKJ) *(u32x4*)(sb + j * 9216 + lrow * 144 + lkc * 16) = rg[j];
;                 else { unsigned char* d = sb + VT_OFF + (lrow + 64 * (j - NKJ)) * 136 + lkc * 16; u32x2 a, c; a.x = rg[j].x; a.y = rg[j].y; c.x = rg[j].z; c.y = rg[j].w; *(u32x2*)d = a; *(u32x2*)(d + 8) = c; }
;             }
;             if (MODE == 1 && tid < 64) *(float*)(sb + CK_OFF + tid * 4) = ckr;
;         };
;         const unsigned koff = cmap * 9216 + r32 * 144 + hh * 16;
;         const unsigned voff = VT_OFF + r32 * 136 + hh * 8;
; __global__ void __launch_bounds__(NTHREADS) fwd_megakernel(Params p) {
;     ...
;     PH(10) attn_phase<2>(p, lds);
.LBB0_3589:
	s_or_b64 exec, exec, s[2:3]
	v_cmp_gt_i32_e32 vcc, 11, v1
	v_cmp_lt_i32_e64 s[2:3], 10, v5
	s_and_b64 s[0:1], vcc, s[2:3]
	s_and_saveexec_b64 s[8:9], s[0:1]
	s_cbranch_execz .LBB0_3644
	v_readfirstlane_b32 s32, v0
	s_nop 3
	s_cmp_lt_u32 s32, 0x100
	s_cbranch_scc1 .Lprio_skip_a2
	s_setprio 1
.Lprio_skip_a2:
	s_add_u32 s10, s42, 0x7200000
	s_addc_u32 s11, s43, 0
	s_add_u32 s12, s42, 0x19200000
	s_addc_u32 s13, s43, 0
	v_and_b32_e32 v1, 7, v0
	s_add_u32 s14, s42, 0x1d200000
	v_mov_b32_e32 v3, 0
	s_addc_u32 s15, s43, 0
	s_not_b32 s0, s33
	v_lshlrev_b32_e32 v166, 4, v1
	v_mov_b32_e32 v167, v3
	s_add_i32 s28, s86, s0
	v_lshl_add_u64 v[4:5], s[42:43], 0, v[166:167]
	s_mov_b64 s[0:1], 0x15200000
	v_lshrrev_b32_e32 v2, 1, v0
	v_lshl_add_u64 v[168:169], v[4:5], 0, s[0:1]
	s_movk_i32 s1, 0x90
	v_and_b32_e32 v195, 0xe0, v2
	v_mad_u32_u24 v35, v171, s1, 0
	v_and_b32_e32 v2, 0x1f8, v0
	v_sub_u32_e32 v198, v35, v2
	v_mov_b32_e32 v2, 0x3f80
	v_cmp_eq_u32_e64 s[2:3], 0, v107
	v_lshlrev_b32_e32 v34, 3, v1
	v_mul_u32_u24_e32 v1, 0x90, v194
	v_cndmask_b32_e64 v130, 0, v2, s[2:3]
	v_mov_b32_e32 v2, 0xd800
	v_add_u32_e32 v36, 0, v84
	v_mad_u32_u24 v201, v171, s1, v2
	v_mad_u32_u24 v2, v194, s1, v84
	v_mov_b32_e32 v4, 0x9000
	v_mov_b32_e32 v18, v3
	v_mov_b32_e32 v19, v3
	v_mov_b32_e32 v20, v3
	v_mov_b32_e32 v21, v3
	v_mov_b32_e32 v22, v3
	v_mov_b32_e32 v23, v3
	v_mov_b32_e32 v24, v3
	v_mov_b32_e32 v25, v3
	v_mov_b32_e32 v26, v3
	v_mov_b32_e32 v27, v3
	v_mov_b32_e32 v28, v3
	v_mov_b32_e32 v29, v3
	v_mov_b32_e32 v30, v3
	v_mov_b32_e32 v31, v3
	v_mov_b32_e32 v32, v3
	v_mov_b32_e32 v33, v3
	v_add_u32_e32 v202, 0x4800, v2
	v_mad_u32_u24 v203, v171, s1, v4
	v_add_u32_e32 v204, 0x9000, v2
	v_mov_b32_e32 v2, v3
	v_mov_b32_e32 v4, v3
	v_mov_b32_e32 v5, v3
	v_mov_b32_e32 v6, v3
	v_mov_b32_e32 v7, v3
	v_mov_b32_e32 v8, v3
	v_mov_b32_e32 v9, v3
	v_mov_b32_e32 v10, v3
	v_mov_b32_e32 v11, v3
	v_mov_b32_e32 v12, v3
	v_mov_b32_e32 v13, v3
	v_mov_b32_e32 v14, v3
	v_mov_b32_e32 v15, v3
	v_mov_b32_e32 v16, v3
	v_mov_b32_e32 v17, v3
	v_lshlrev_b32_e32 v174, 1, v34
	v_add_u32_e32 v205, v35, v166
	s_movk_i32 s1, 0x6c00
	v_add_u32_e32 v207, v36, v1
	v_mov_b64_e32 v[48:49], v[32:33]
	v_mul_u32_u24_e32 v196, 0x88, v194
	s_mov_b32 s0, 0
	v_mul_u32_u24_e32 v197, 0x88, v171
	v_mov_b32_e32 v131, v3
	v_mov_b32_e32 v132, v3
	v_mov_b32_e32 v133, v3
	v_lshlrev_b32_e32 v170, 2, v107
	v_add_u32_e32 v199, 0, v82
	v_add_u32_e32 v200, 0, v166
	s_movk_i32 s29, 0x1c00
	v_lshlrev_b32_e32 v172, 1, v82
	s_mov_b64 s[16:17], 0x800
	s_movk_i32 s30, 0x2400
	v_add3_u32 v206, v198, v166, s1
	s_mov_b32 s31, 0xefa18f08
	s_mov_b32 s34, 0xff800000
	v_mov_b32_e32 v177, 0x41000000
	s_mov_b32 s35, 0xb400
	s_mov_b32 s36, 0xfc00
	s_mov_b64 s[18:19], 0x100
	s_mov_b64 s[20:21], 0xe0000
	s_mov_b32 s37, 0
	v_mov_b64_e32 v[46:47], v[30:31]
	v_mov_b64_e32 v[44:45], v[28:29]
	v_mov_b64_e32 v[42:43], v[26:27]
	v_mov_b64_e32 v[40:41], v[24:25]
	v_mov_b64_e32 v[38:39], v[22:23]
	v_mov_b64_e32 v[36:37], v[20:21]
	v_mov_b64_e32 v[34:35], v[18:19]
	v_mov_b64_e32 v[32:33], v[16:17]
	v_mov_b64_e32 v[30:31], v[14:15]
	v_mov_b64_e32 v[28:29], v[12:13]
	v_mov_b64_e32 v[26:27], v[10:11]
	v_mov_b64_e32 v[24:25], v[8:9]
	v_mov_b64_e32 v[22:23], v[6:7]
	v_mov_b64_e32 v[20:21], v[4:5]
	v_mov_b64_e32 v[18:19], v[2:3]
	s_branch .LBB0_3594

; #define SYNC(k) if (p.ph_lo <= (k) && (k) + 1 < p.ph_hi) { if ((k) == 0) grid.sync(); else gbar(bctr, bgen, gridDim.x); }
; DI void gbar(unsigned* ctr, unsigned& gen, unsigned G) {
;     asm volatile("s_waitcnt vmcnt(0)" ::: "memory");
;     __syncthreads();
;     gen += 1;
;     if (threadIdx.x == 0) {
;         __builtin_amdgcn_fence(__ATOMIC_RELEASE, "agent");
;         asm volatile("s_waitcnt vmcnt(0)" ::: "memory");
;         __hip_atomic_fetch_add(ctr, 1u, __ATOMIC_RELAXED, __HIP_MEMORY_SCOPE_AGENT);
;         while (__hip_atomic_load(ctr, __ATOMIC_RELAXED, __HIP_MEMORY_SCOPE_AGENT) < gen * G) __builtin_amdgcn_s_sleep(32);
; __global__ void __launch_bounds__(NTHREADS) fwd_megakernel(Params p) {
;     ...
;     SYNC(10)
.LBB0_3644:
	s_or_b64 exec, exec, s[8:9]
	s_setprio 0
	v_cmp_gt_i32_e32 vcc, 11, v1
	v_cmp_lt_i32_e64 s[2:3], 11, v5
	s_and_b64 s[0:1], vcc, s[2:3]
	s_and_saveexec_b64 s[2:3], s[0:1]
	s_cbranch_execz .LBB0_3653
	s_waitcnt vmcnt(0)
	v_and_b32_e32 v2, 0x3ff, v0
	v_add_u32_e32 v210, 1, v210
	v_cmp_eq_u32_e32 vcc, 0, v2
	s_waitcnt vmcnt(0)
	s_barrier
	s_and_saveexec_b64 s[4:5], vcc
	s_cbranch_execz .LBB0_3652
	s_mov_b64 s[6:7], exec
	buffer_wbl2 sc1
	s_waitcnt vmcnt(0)
	v_mbcnt_lo_u32_b32 v1, s6, 0
	v_mbcnt_hi_u32_b32 v1, s7, v1
	v_cmp_eq_u32_e32 vcc, 0, v1
	s_and_saveexec_b64 s[8:9], vcc
	s_cbranch_execz .LBB0_3648
	s_bcnt1_i32_b64 s0, s[6:7]
	v_mov_b32_e32 v1, 0
	v_mov_b32_e32 v2, s0
	global_atomic_add v1, v2, s[62:63]
